# v19 + in-proj gate epilogue: 32 dwordx2 stores -> 16 dwordx4 via v_permlane16_swap row exchange (same bytes, same addresses)
# speedup vs baseline: 1.0060x; 1.0060x over previous
.LBB0_808:
	v_mbcnt_lo_u32_b32 v178, -1, 0
	v_mbcnt_hi_u32_b32 v178, -1, v178
	v_and_b32_e32 v178, 16, v178
	v_mul_u32_u24_e32 v178, 0xff8, v178
	v_lshrrev_b32_e32 v178, 4, v178
	v_mov_b32_e32 v179, 0
	v_mul_f32_e32 v137, 0xbfb8aa3b, v122
	v_exp_f32_e32 v137, v137
	v_mul_f32_e32 v139, 0xbfb8aa3b, v126
	v_exp_f32_e32 v144, v139
	v_mul_f32_e32 v139, 0xbfb8aa3b, v118
	v_add_f32_e32 v137, 1.0, v137
	v_rcp_f32_e32 v156, v137
	v_mul_f32_e32 v137, 0xbfb8aa3b, v123
	v_exp_f32_e32 v137, v137
	v_exp_f32_e32 v146, v139
	v_mul_f32_e32 v139, 0xbfb8aa3b, v114
	v_exp_f32_e32 v154, v139
	v_mul_f32_e32 v139, 0xbfb8aa3b, v127
	v_exp_f32_e32 v145, v139
	v_mul_f32_e32 v139, 0xbfb8aa3b, v119
	v_exp_f32_e32 v147, v139
	v_add_f32_e32 v137, 1.0, v137
	v_rcp_f32_e32 v157, v137
	v_mul_f32_e32 v137, 0xbfb8aa3b, v124
	v_mul_f32_e32 v139, 0xbfb8aa3b, v115
	v_pk_add_f32 v[144:145], v[144:145], 1.0 op_sel_hi:[1,0]
	v_exp_f32_e32 v137, v137
	v_exp_f32_e32 v155, v139
	v_rcp_f32_e32 v158, v144
	v_rcp_f32_e32 v159, v145
	v_pk_add_f32 v[146:147], v[146:147], 1.0 op_sel_hi:[1,0]
	v_pk_mul_f32 v[144:145], v[144:145], v[156:157]
	v_rcp_f32_e32 v156, v146
	v_rcp_f32_e32 v157, v147
	v_add_f32_e32 v137, 1.0, v137
	v_pk_mul_f32 v[158:159], v[146:147], v[158:159]
	v_pk_add_f32 v[146:147], v[154:155], 1.0 op_sel_hi:[1,0]
	v_mul_f32_e32 v143, 0xbfb8aa3b, v128
	v_rcp_f32_e32 v162, v137
	v_mul_f32_e32 v137, 0xbfb8aa3b, v125
	v_rcp_f32_e32 v139, v146
	v_pk_mul_f32 v[154:155], v[146:147], v[156:157]
	v_exp_f32_e32 v146, v143
	v_mul_f32_e32 v143, 0xbfb8aa3b, v120
	v_exp_f32_e32 v137, v137
	v_exp_f32_e32 v156, v143
	v_mul_f32_e32 v143, 0xbfb8aa3b, v116
	v_exp_f32_e32 v160, v143
	v_mul_f32_e32 v143, 0xbfb8aa3b, v129
	v_rcp_f32_e32 v141, v147
	v_exp_f32_e32 v147, v143
	v_mul_f32_e32 v143, 0xbfb8aa3b, v121
	v_exp_f32_e32 v157, v143
	v_add_f32_e32 v137, 1.0, v137
	v_rcp_f32_e32 v163, v137
	v_mul_f32_e32 v143, 0xbfb8aa3b, v117
	v_pk_add_f32 v[146:147], v[146:147], 1.0 op_sel_hi:[1,0]
	v_exp_f32_e32 v161, v143
	v_rcp_f32_e32 v164, v146
	v_rcp_f32_e32 v165, v147
	v_pk_add_f32 v[156:157], v[156:157], 1.0 op_sel_hi:[1,0]
	v_pk_mul_f32 v[146:147], v[146:147], v[162:163]
	v_rcp_f32_e32 v162, v156
	v_rcp_f32_e32 v163, v157
	v_lshl_add_u32 v0, s16, 6, v151
	v_pk_mul_f32 v[156:157], v[156:157], v[164:165]
	v_pk_add_f32 v[160:161], v[160:161], 1.0 op_sel_hi:[1,0]
	v_ashrrev_i32_e32 v137, 31, v136
	v_cvt_pk_bf16_f32 v171, v146, v147
	v_readlane_b32 s8, v253, 13
	v_lshlrev_b64 v[146:147], 1, v[0:1]
	v_mul_f32_e32 v0, 0xbfb8aa3b, v110
	v_rcp_f32_e32 v143, v160
	v_rcp_f32_e32 v153, v161
	v_pk_mul_f32 v[160:161], v[160:161], v[162:163]
	v_lshlrev_b64 v[162:163], 13, v[136:137]
	v_readlane_b32 s9, v253, 14
	v_exp_f32_e32 v0, v0
	v_cvt_pk_bf16_f32 v170, v144, v145
	v_lshl_add_u64 v[144:145], s[8:9], 0, v[162:163]
	v_lshl_add_u64 v[144:145], v[144:145], 0, v[146:147]
	s_movk_i32 s2, 0x1000
	v_cvt_pk_bf16_f32 v174, v158, v159
	v_cvt_pk_bf16_f32 v175, v156, v157
	v_add_co_u32_e32 v156, vcc, s2, v144
	v_cvt_pk_bf16_f32 v172, v154, v155
	v_cvt_pk_bf16_f32 v173, v160, v161
	v_addc_co_u32_e32 v157, vcc, 0, v145, vcc
	v_add_f32_e32 v0, 1.0, v0
	v_lshl_add_u64 v[180:181], v[156:157], 0, v[178:179]
	v_cvt_pk_bf16_f32 v176, v139, v141
	v_cvt_pk_bf16_f32 v177, v143, v153
	v_mul_f32_e32 v137, 0xbfb8aa3b, v106
	v_rcp_f32_e32 v160, v0
	v_mul_f32_e32 v0, 0xbfb8aa3b, v111
	v_exp_f32_e32 v154, v137
	v_mul_f32_e32 v137, 0xbfb8aa3b, v102
	v_exp_f32_e32 v0, v0
	v_exp_f32_e32 v156, v137
	v_mul_f32_e32 v137, 0xbfb8aa3b, v98
	v_exp_f32_e32 v158, v137
	v_mul_f32_e32 v137, 0xbfb8aa3b, v107
	v_exp_f32_e32 v155, v137
	v_mul_f32_e32 v137, 0xbfb8aa3b, v103
	v_exp_f32_e32 v157, v137
	v_add_f32_e32 v0, 1.0, v0
	v_rcp_f32_e32 v161, v0
	v_mul_f32_e32 v139, 0xbfb8aa3b, v112
	v_mul_f32_e32 v137, 0xbfb8aa3b, v99
	v_exp_f32_e32 v139, v139
	v_exp_f32_e32 v159, v137
	v_pk_add_f32 v[154:155], v[154:155], 1.0 op_sel_hi:[1,0]
	v_pk_add_f32 v[156:157], v[156:157], 1.0 op_sel_hi:[1,0]
	v_rcp_f32_e32 v162, v154
	v_rcp_f32_e32 v163, v155
	v_pk_mul_f32 v[154:155], v[154:155], v[160:161]
	v_rcp_f32_e32 v160, v156
	v_rcp_f32_e32 v161, v157
	v_add_f32_e32 v139, 1.0, v139
	v_pk_add_f32 v[158:159], v[158:159], 1.0 op_sel_hi:[1,0]
	v_mul_f32_e32 v141, 0xbfb8aa3b, v108
	v_rcp_f32_e32 v166, v139
	v_mul_f32_e32 v139, 0xbfb8aa3b, v113
	v_rcp_f32_e32 v0, v158
	v_rcp_f32_e32 v137, v159
	v_pk_mul_f32 v[158:159], v[158:159], v[160:161]
	v_exp_f32_e32 v160, v141
	v_mul_f32_e32 v141, 0xbfb8aa3b, v104
	v_exp_f32_e32 v139, v139
	v_pk_mul_f32 v[156:157], v[156:157], v[162:163]
	v_exp_f32_e32 v162, v141
	v_mul_f32_e32 v141, 0xbfb8aa3b, v100
	s_nop 1
	v_permlane16_swap_b32_e32 v170, v172
	v_permlane16_swap_b32_e32 v171, v173
	v_permlane16_swap_b32_e32 v174, v176
	v_permlane16_swap_b32_e32 v175, v177
	global_store_dwordx4 v[180:181], v[170:173], off offset:-4096
	global_store_dwordx4 v[180:181], v[174:177], off offset:-2048
	v_exp_f32_e32 v164, v141
	v_mul_f32_e32 v141, 0xbfb8aa3b, v109
	v_exp_f32_e32 v161, v141
	v_mul_f32_e32 v141, 0xbfb8aa3b, v105
	v_exp_f32_e32 v163, v141
	v_add_f32_e32 v139, 1.0, v139
	v_rcp_f32_e32 v167, v139
	v_mul_f32_e32 v141, 0xbfb8aa3b, v101
	v_exp_f32_e32 v165, v141
	v_pk_add_f32 v[160:161], v[160:161], 1.0 op_sel_hi:[1,0]
	v_pk_add_f32 v[162:163], v[162:163], 1.0 op_sel_hi:[1,0]
	v_rcp_f32_e32 v168, v160
	v_rcp_f32_e32 v169, v161
	v_pk_mul_f32 v[160:161], v[160:161], v[166:167]
	v_rcp_f32_e32 v166, v162
	v_rcp_f32_e32 v167, v163
	v_pk_add_f32 v[164:165], v[164:165], 1.0 op_sel_hi:[1,0]
	v_ashrrev_i32_e32 v143, 31, v142
	v_rcp_f32_e32 v139, v164
	v_rcp_f32_e32 v141, v165
	v_pk_mul_f32 v[164:165], v[164:165], v[166:167]
	v_lshlrev_b64 v[166:167], 13, v[142:143]
	v_cvt_pk_bf16_f32 v170, v154, v155
	v_cvt_pk_bf16_f32 v171, v160, v161
	v_lshl_add_u64 v[160:161], s[8:9], 0, v[166:167]
	v_pk_mul_f32 v[162:163], v[162:163], v[168:169]
	v_lshl_add_u64 v[160:161], v[160:161], 0, v[146:147]
	v_lshl_add_u64 v[180:181], v[160:161], 0, v[178:179]
	v_cvt_pk_bf16_f32 v174, v156, v157
	v_cvt_pk_bf16_f32 v175, v162, v163
	v_add_co_u32_e32 v156, vcc, s2, v160
	v_cvt_pk_bf16_f32 v172, v158, v159
	v_cvt_pk_bf16_f32 v173, v164, v165
	v_addc_co_u32_e32 v157, vcc, 0, v161, vcc
	v_cvt_pk_bf16_f32 v176, v0, v137
	v_mul_f32_e32 v0, 0xbfb8aa3b, v94
	v_exp_f32_e32 v0, v0
	v_cvt_pk_bf16_f32 v177, v139, v141
	v_mul_f32_e32 v137, 0xbfb8aa3b, v90
	s_nop 1
	v_permlane16_swap_b32_e32 v170, v172
	v_permlane16_swap_b32_e32 v171, v173
	v_permlane16_swap_b32_e32 v174, v176
	v_permlane16_swap_b32_e32 v175, v177
	global_store_dwordx4 v[180:181], v[170:173], off
	global_store_dwordx4 v[180:181], v[174:177], off offset:2048
	v_add_f32_e32 v0, 1.0, v0
	v_rcp_f32_e32 v160, v0
	v_mul_f32_e32 v0, 0xbfb8aa3b, v95
	v_exp_f32_e32 v154, v137
	v_mul_f32_e32 v137, 0xbfb8aa3b, v86
	v_exp_f32_e32 v0, v0
	v_exp_f32_e32 v156, v137
	v_mul_f32_e32 v137, 0xbfb8aa3b, v82
	v_exp_f32_e32 v158, v137
	v_mul_f32_e32 v137, 0xbfb8aa3b, v91
	v_exp_f32_e32 v155, v137
	v_mul_f32_e32 v137, 0xbfb8aa3b, v87
	v_exp_f32_e32 v157, v137
	v_add_f32_e32 v0, 1.0, v0
	v_rcp_f32_e32 v161, v0
	v_mul_f32_e32 v139, 0xbfb8aa3b, v96
	v_mul_f32_e32 v137, 0xbfb8aa3b, v83
	v_exp_f32_e32 v139, v139
	v_exp_f32_e32 v159, v137
	v_pk_add_f32 v[154:155], v[154:155], 1.0 op_sel_hi:[1,0]
	v_pk_add_f32 v[156:157], v[156:157], 1.0 op_sel_hi:[1,0]
	v_rcp_f32_e32 v162, v154
	v_rcp_f32_e32 v163, v155
	v_pk_mul_f32 v[154:155], v[154:155], v[160:161]
	v_rcp_f32_e32 v160, v156
	v_rcp_f32_e32 v161, v157
	v_add_f32_e32 v139, 1.0, v139
	v_pk_add_f32 v[158:159], v[158:159], 1.0 op_sel_hi:[1,0]
	v_mul_f32_e32 v141, 0xbfb8aa3b, v92
	v_rcp_f32_e32 v166, v139
	v_mul_f32_e32 v139, 0xbfb8aa3b, v97
	v_rcp_f32_e32 v0, v158
	v_rcp_f32_e32 v137, v159
	v_pk_mul_f32 v[158:159], v[158:159], v[160:161]
	v_exp_f32_e32 v160, v141
	v_mul_f32_e32 v141, 0xbfb8aa3b, v88
	v_exp_f32_e32 v139, v139
	v_pk_mul_f32 v[156:157], v[156:157], v[162:163]
	v_exp_f32_e32 v162, v141
	v_mul_f32_e32 v141, 0xbfb8aa3b, v84
	v_exp_f32_e32 v164, v141
	v_mul_f32_e32 v141, 0xbfb8aa3b, v93
	v_exp_f32_e32 v161, v141
	v_mul_f32_e32 v141, 0xbfb8aa3b, v89
	v_exp_f32_e32 v163, v141
	v_add_f32_e32 v139, 1.0, v139
	v_rcp_f32_e32 v167, v139
	v_mul_f32_e32 v141, 0xbfb8aa3b, v85
	v_exp_f32_e32 v165, v141
	v_pk_add_f32 v[160:161], v[160:161], 1.0 op_sel_hi:[1,0]
	v_pk_add_f32 v[162:163], v[162:163], 1.0 op_sel_hi:[1,0]
	v_rcp_f32_e32 v168, v160
	v_rcp_f32_e32 v169, v161
	v_pk_mul_f32 v[160:161], v[160:161], v[166:167]
	v_rcp_f32_e32 v166, v162
	v_rcp_f32_e32 v167, v163
	v_pk_add_f32 v[164:165], v[164:165], 1.0 op_sel_hi:[1,0]
	v_ashrrev_i32_e32 v141, 31, v140
	v_rcp_f32_e32 v139, v164
	v_rcp_f32_e32 v143, v165
	v_pk_mul_f32 v[164:165], v[164:165], v[166:167]
	v_lshlrev_b64 v[166:167], 13, v[140:141]
	v_cvt_pk_bf16_f32 v170, v154, v155
	v_cvt_pk_bf16_f32 v171, v160, v161
	v_lshl_add_u64 v[160:161], s[8:9], 0, v[166:167]
	v_pk_mul_f32 v[162:163], v[162:163], v[168:169]
	v_lshl_add_u64 v[160:161], v[160:161], 0, v[146:147]
	v_lshl_add_u64 v[180:181], v[160:161], 0, v[178:179]
	v_cvt_pk_bf16_f32 v174, v156, v157
	v_cvt_pk_bf16_f32 v175, v162, v163
	v_add_co_u32_e32 v156, vcc, s2, v160
	v_cvt_pk_bf16_f32 v172, v158, v159
	v_cvt_pk_bf16_f32 v173, v164, v165
	v_addc_co_u32_e32 v157, vcc, 0, v161, vcc
	v_cvt_pk_bf16_f32 v176, v0, v137
	v_mul_f32_e32 v0, 0xbfb8aa3b, v78
	v_exp_f32_e32 v0, v0
	v_cvt_pk_bf16_f32 v177, v139, v143
	v_mul_f32_e32 v137, 0xbfb8aa3b, v74
	s_nop 1
	v_permlane16_swap_b32_e32 v170, v172
	v_permlane16_swap_b32_e32 v171, v173
	v_permlane16_swap_b32_e32 v174, v176
	v_permlane16_swap_b32_e32 v175, v177
	global_store_dwordx4 v[180:181], v[170:173], off
	global_store_dwordx4 v[180:181], v[174:177], off offset:2048
	v_add_f32_e32 v0, 1.0, v0
	v_rcp_f32_e32 v160, v0
	v_mul_f32_e32 v0, 0xbfb8aa3b, v79
	v_exp_f32_e32 v154, v137
	v_mul_f32_e32 v137, 0xbfb8aa3b, v70
	v_exp_f32_e32 v0, v0
	v_exp_f32_e32 v156, v137
	v_mul_f32_e32 v137, 0xbfb8aa3b, v66
	v_exp_f32_e32 v158, v137
	v_mul_f32_e32 v137, 0xbfb8aa3b, v75
	v_exp_f32_e32 v155, v137
	v_mul_f32_e32 v137, 0xbfb8aa3b, v71
	v_exp_f32_e32 v157, v137
	v_add_f32_e32 v0, 1.0, v0
	v_rcp_f32_e32 v161, v0
	v_mul_f32_e32 v139, 0xbfb8aa3b, v80
	v_mul_f32_e32 v137, 0xbfb8aa3b, v67
	v_exp_f32_e32 v139, v139
	v_exp_f32_e32 v159, v137
	v_pk_add_f32 v[154:155], v[154:155], 1.0 op_sel_hi:[1,0]
	v_pk_add_f32 v[156:157], v[156:157], 1.0 op_sel_hi:[1,0]
	v_rcp_f32_e32 v162, v154
	v_rcp_f32_e32 v163, v155
	v_pk_mul_f32 v[154:155], v[154:155], v[160:161]
	v_rcp_f32_e32 v160, v156
	v_rcp_f32_e32 v161, v157
	v_add_f32_e32 v139, 1.0, v139
	v_pk_add_f32 v[158:159], v[158:159], 1.0 op_sel_hi:[1,0]
	v_mul_f32_e32 v141, 0xbfb8aa3b, v76
	v_rcp_f32_e32 v166, v139
	v_mul_f32_e32 v139, 0xbfb8aa3b, v81
	v_rcp_f32_e32 v0, v158
	v_rcp_f32_e32 v137, v159
	v_pk_mul_f32 v[158:159], v[158:159], v[160:161]
	v_exp_f32_e32 v160, v141
	v_mul_f32_e32 v141, 0xbfb8aa3b, v72
	v_exp_f32_e32 v139, v139
	v_pk_mul_f32 v[156:157], v[156:157], v[162:163]
	v_exp_f32_e32 v162, v141
	v_mul_f32_e32 v141, 0xbfb8aa3b, v68
	v_exp_f32_e32 v164, v141
	v_mul_f32_e32 v141, 0xbfb8aa3b, v77
	v_exp_f32_e32 v161, v141
	v_mul_f32_e32 v141, 0xbfb8aa3b, v73
	v_exp_f32_e32 v163, v141
	v_add_f32_e32 v139, 1.0, v139
	v_rcp_f32_e32 v167, v139
	v_mul_f32_e32 v141, 0xbfb8aa3b, v69
	v_exp_f32_e32 v165, v141
	v_pk_add_f32 v[160:161], v[160:161], 1.0 op_sel_hi:[1,0]
	v_pk_add_f32 v[162:163], v[162:163], 1.0 op_sel_hi:[1,0]
	v_rcp_f32_e32 v168, v160
	v_rcp_f32_e32 v169, v161
	v_pk_mul_f32 v[160:161], v[160:161], v[166:167]
	v_rcp_f32_e32 v166, v162
	v_rcp_f32_e32 v167, v163
	v_pk_add_f32 v[164:165], v[164:165], 1.0 op_sel_hi:[1,0]
	v_ashrrev_i32_e32 v139, 31, v138
	v_rcp_f32_e32 v141, v164
	v_rcp_f32_e32 v143, v165
	v_pk_mul_f32 v[164:165], v[164:165], v[166:167]
	v_lshlrev_b64 v[166:167], 13, v[138:139]
	v_cvt_pk_bf16_f32 v170, v154, v155
	v_cvt_pk_bf16_f32 v171, v160, v161
	v_lshl_add_u64 v[160:161], s[8:9], 0, v[166:167]
	v_pk_mul_f32 v[162:163], v[162:163], v[168:169]
	v_lshl_add_u64 v[146:147], v[160:161], 0, v[146:147]
	v_lshl_add_u64 v[180:181], v[146:147], 0, v[178:179]
	v_cvt_pk_bf16_f32 v174, v156, v157
	v_cvt_pk_bf16_f32 v175, v162, v163
	v_add_co_u32_e32 v146, vcc, s2, v146
	v_cvt_pk_bf16_f32 v172, v158, v159
	v_cvt_pk_bf16_f32 v173, v164, v165
	v_addc_co_u32_e32 v147, vcc, 0, v147, vcc
	v_cvt_pk_bf16_f32 v176, v0, v137
	v_mul_f32_e32 v0, 0xbfb8aa3b, v62
	v_exp_f32_e32 v0, v0
	v_cvt_pk_bf16_f32 v177, v141, v143
	v_mul_f32_e32 v137, 0xbfb8aa3b, v58
	s_nop 1
	v_permlane16_swap_b32_e32 v170, v172
	v_permlane16_swap_b32_e32 v171, v173
	v_permlane16_swap_b32_e32 v174, v176
	v_permlane16_swap_b32_e32 v175, v177
	global_store_dwordx4 v[180:181], v[170:173], off
	global_store_dwordx4 v[180:181], v[174:177], off offset:2048
	v_add_f32_e32 v0, 1.0, v0
	v_rcp_f32_e32 v158, v0
	v_mul_f32_e32 v0, 0xbfb8aa3b, v63
	v_exp_f32_e32 v146, v137
	v_mul_f32_e32 v137, 0xbfb8aa3b, v54
	v_exp_f32_e32 v0, v0
	v_exp_f32_e32 v154, v137
	v_mul_f32_e32 v137, 0xbfb8aa3b, v50
	v_exp_f32_e32 v156, v137
	v_mul_f32_e32 v137, 0xbfb8aa3b, v59
	v_exp_f32_e32 v147, v137
	v_mul_f32_e32 v137, 0xbfb8aa3b, v55
	v_exp_f32_e32 v155, v137
	v_add_f32_e32 v0, 1.0, v0
	v_rcp_f32_e32 v159, v0
	v_mul_f32_e32 v139, 0xbfb8aa3b, v64
	v_mul_f32_e32 v137, 0xbfb8aa3b, v51
	v_exp_f32_e32 v139, v139
	v_exp_f32_e32 v157, v137
	v_pk_add_f32 v[146:147], v[146:147], 1.0 op_sel_hi:[1,0]
	v_pk_add_f32 v[154:155], v[154:155], 1.0 op_sel_hi:[1,0]
	v_rcp_f32_e32 v160, v146
	v_rcp_f32_e32 v161, v147
	v_pk_mul_f32 v[146:147], v[146:147], v[158:159]
	v_rcp_f32_e32 v158, v154
	v_rcp_f32_e32 v159, v155
	v_add_f32_e32 v139, 1.0, v139
	v_pk_add_f32 v[156:157], v[156:157], 1.0 op_sel_hi:[1,0]
	v_mul_f32_e32 v141, 0xbfb8aa3b, v60
	v_rcp_f32_e32 v164, v139
	v_mul_f32_e32 v139, 0xbfb8aa3b, v65
	v_rcp_f32_e32 v0, v156
	v_rcp_f32_e32 v137, v157
	v_pk_mul_f32 v[156:157], v[156:157], v[158:159]
	v_exp_f32_e32 v158, v141
	v_mul_f32_e32 v141, 0xbfb8aa3b, v56
	v_exp_f32_e32 v139, v139
	v_pk_mul_f32 v[154:155], v[154:155], v[160:161]
	v_exp_f32_e32 v160, v141
	v_mul_f32_e32 v141, 0xbfb8aa3b, v52
	v_exp_f32_e32 v162, v141
	v_mul_f32_e32 v141, 0xbfb8aa3b, v61
	v_exp_f32_e32 v159, v141
	v_mul_f32_e32 v141, 0xbfb8aa3b, v57
	v_exp_f32_e32 v161, v141
	v_add_f32_e32 v139, 1.0, v139
	v_rcp_f32_e32 v165, v139
	v_mul_f32_e32 v141, 0xbfb8aa3b, v53
	v_exp_f32_e32 v163, v141
	v_pk_add_f32 v[158:159], v[158:159], 1.0 op_sel_hi:[1,0]
	v_pk_add_f32 v[160:161], v[160:161], 1.0 op_sel_hi:[1,0]
	v_rcp_f32_e32 v166, v158
	v_rcp_f32_e32 v167, v159
	v_pk_mul_f32 v[158:159], v[158:159], v[164:165]
	v_rcp_f32_e32 v164, v160
	v_rcp_f32_e32 v165, v161
	s_mov_b64 s[8:9], 0x100000
	v_pk_add_f32 v[162:163], v[162:163], 1.0 op_sel_hi:[1,0]
	v_cvt_pk_bf16_f32 v170, v146, v147
	v_cvt_pk_bf16_f32 v171, v158, v159
	v_lshl_add_u64 v[158:159], v[144:145], 0, s[8:9]
	s_mov_b32 s8, 0x101000
	v_rcp_f32_e32 v139, v162
	v_rcp_f32_e32 v141, v163
	v_pk_mul_f32 v[162:163], v[162:163], v[164:165]
	v_add_co_u32_e32 v164, vcc, s8, v144
	v_pk_mul_f32 v[160:161], v[160:161], v[166:167]
	s_nop 0
	v_addc_co_u32_e32 v165, vcc, 0, v145, vcc
	v_lshl_add_u64 v[180:181], v[164:165], 0, v[178:179]
	v_cvt_pk_bf16_f32 v174, v154, v155
	v_cvt_pk_bf16_f32 v175, v160, v161
	v_cvt_pk_bf16_f32 v172, v156, v157
	v_cvt_pk_bf16_f32 v173, v162, v163
	v_cvt_pk_bf16_f32 v176, v0, v137
	v_mul_f32_e32 v0, 0xbfb8aa3b, v46
	v_exp_f32_e32 v0, v0
	v_cvt_pk_bf16_f32 v177, v139, v141
	v_mul_f32_e32 v137, 0xbfb8aa3b, v42
	s_nop 1
	v_permlane16_swap_b32_e32 v170, v172
	v_permlane16_swap_b32_e32 v171, v173
	v_permlane16_swap_b32_e32 v174, v176
	v_permlane16_swap_b32_e32 v175, v177
	global_store_dwordx4 v[180:181], v[170:173], off offset:-4096
	global_store_dwordx4 v[180:181], v[174:177], off offset:-2048
	v_add_f32_e32 v0, 1.0, v0
	v_rcp_f32_e32 v158, v0
	v_mul_f32_e32 v0, 0xbfb8aa3b, v47
	v_exp_f32_e32 v146, v137
	v_mul_f32_e32 v137, 0xbfb8aa3b, v38
	v_exp_f32_e32 v0, v0
	v_exp_f32_e32 v154, v137
	v_mul_f32_e32 v137, 0xbfb8aa3b, v34
	v_exp_f32_e32 v156, v137
	v_mul_f32_e32 v137, 0xbfb8aa3b, v43
	v_exp_f32_e32 v147, v137
	v_mul_f32_e32 v137, 0xbfb8aa3b, v39
	v_exp_f32_e32 v155, v137
	v_add_f32_e32 v0, 1.0, v0
	v_rcp_f32_e32 v159, v0
	v_mul_f32_e32 v139, 0xbfb8aa3b, v48
	v_mul_f32_e32 v137, 0xbfb8aa3b, v35
	v_exp_f32_e32 v139, v139
	v_exp_f32_e32 v157, v137
	v_pk_add_f32 v[146:147], v[146:147], 1.0 op_sel_hi:[1,0]
	v_pk_add_f32 v[154:155], v[154:155], 1.0 op_sel_hi:[1,0]
	v_rcp_f32_e32 v160, v146
	v_rcp_f32_e32 v161, v147
	v_pk_mul_f32 v[146:147], v[146:147], v[158:159]
	v_rcp_f32_e32 v158, v154
	v_rcp_f32_e32 v159, v155
	v_add_f32_e32 v139, 1.0, v139
	v_pk_add_f32 v[156:157], v[156:157], 1.0 op_sel_hi:[1,0]
	v_mul_f32_e32 v141, 0xbfb8aa3b, v44
	v_rcp_f32_e32 v164, v139
	v_mul_f32_e32 v139, 0xbfb8aa3b, v49
	v_rcp_f32_e32 v0, v156
	v_rcp_f32_e32 v137, v157
	v_pk_mul_f32 v[156:157], v[156:157], v[158:159]
	v_exp_f32_e32 v158, v141
	v_mul_f32_e32 v141, 0xbfb8aa3b, v40
	v_exp_f32_e32 v139, v139
	v_pk_mul_f32 v[154:155], v[154:155], v[160:161]
	v_exp_f32_e32 v160, v141
	v_mul_f32_e32 v141, 0xbfb8aa3b, v36
	v_exp_f32_e32 v162, v141
	v_mul_f32_e32 v141, 0xbfb8aa3b, v45
	v_exp_f32_e32 v159, v141
	v_mul_f32_e32 v141, 0xbfb8aa3b, v41
	v_exp_f32_e32 v161, v141
	v_add_f32_e32 v139, 1.0, v139
	v_rcp_f32_e32 v165, v139
	v_mul_f32_e32 v141, 0xbfb8aa3b, v37
	v_exp_f32_e32 v163, v141
	v_pk_add_f32 v[158:159], v[158:159], 1.0 op_sel_hi:[1,0]
	v_pk_add_f32 v[160:161], v[160:161], 1.0 op_sel_hi:[1,0]
	v_rcp_f32_e32 v166, v158
	v_rcp_f32_e32 v167, v159
	v_pk_mul_f32 v[158:159], v[158:159], v[164:165]
	v_rcp_f32_e32 v164, v160
	v_rcp_f32_e32 v165, v161
	s_mov_b64 s[8:9], 0x120000
	v_pk_add_f32 v[162:163], v[162:163], 1.0 op_sel_hi:[1,0]
	v_cvt_pk_bf16_f32 v170, v146, v147
	v_cvt_pk_bf16_f32 v171, v158, v159
	v_lshl_add_u64 v[158:159], v[144:145], 0, s[8:9]
	s_mov_b32 s8, 0x121000
	v_rcp_f32_e32 v139, v162
	v_rcp_f32_e32 v141, v163
	v_pk_mul_f32 v[162:163], v[162:163], v[164:165]
	v_add_co_u32_e32 v164, vcc, s8, v144
	v_pk_mul_f32 v[160:161], v[160:161], v[166:167]
	s_nop 0
	v_addc_co_u32_e32 v165, vcc, 0, v145, vcc
	v_lshl_add_u64 v[180:181], v[164:165], 0, v[178:179]
	v_cvt_pk_bf16_f32 v174, v154, v155
	v_cvt_pk_bf16_f32 v175, v160, v161
	v_cvt_pk_bf16_f32 v172, v156, v157
	v_cvt_pk_bf16_f32 v173, v162, v163
	v_cvt_pk_bf16_f32 v176, v0, v137
	v_mul_f32_e32 v0, 0xbfb8aa3b, v30
	v_exp_f32_e32 v0, v0
	v_cvt_pk_bf16_f32 v177, v139, v141
	v_mul_f32_e32 v137, 0xbfb8aa3b, v26
	s_nop 1
	v_permlane16_swap_b32_e32 v170, v172
	v_permlane16_swap_b32_e32 v171, v173
	v_permlane16_swap_b32_e32 v174, v176
	v_permlane16_swap_b32_e32 v175, v177
	global_store_dwordx4 v[180:181], v[170:173], off offset:-4096
	global_store_dwordx4 v[180:181], v[174:177], off offset:-2048
	v_add_f32_e32 v0, 1.0, v0
	v_rcp_f32_e32 v158, v0
	v_mul_f32_e32 v0, 0xbfb8aa3b, v31
	v_exp_f32_e32 v146, v137
	v_mul_f32_e32 v137, 0xbfb8aa3b, v22
	v_exp_f32_e32 v0, v0
	v_exp_f32_e32 v154, v137
	v_mul_f32_e32 v137, 0xbfb8aa3b, v18
	v_exp_f32_e32 v156, v137
	v_mul_f32_e32 v137, 0xbfb8aa3b, v27
	v_exp_f32_e32 v147, v137
	v_mul_f32_e32 v137, 0xbfb8aa3b, v23
	v_exp_f32_e32 v155, v137
	v_add_f32_e32 v0, 1.0, v0
	v_rcp_f32_e32 v159, v0
	v_mul_f32_e32 v139, 0xbfb8aa3b, v32
	v_mul_f32_e32 v137, 0xbfb8aa3b, v19
	v_exp_f32_e32 v139, v139
	v_exp_f32_e32 v157, v137
	v_pk_add_f32 v[146:147], v[146:147], 1.0 op_sel_hi:[1,0]
	v_pk_add_f32 v[154:155], v[154:155], 1.0 op_sel_hi:[1,0]
	v_rcp_f32_e32 v160, v146
	v_rcp_f32_e32 v161, v147
	v_pk_mul_f32 v[146:147], v[146:147], v[158:159]
	v_rcp_f32_e32 v158, v154
	v_rcp_f32_e32 v159, v155
	v_add_f32_e32 v139, 1.0, v139
	v_pk_add_f32 v[156:157], v[156:157], 1.0 op_sel_hi:[1,0]
	v_mul_f32_e32 v141, 0xbfb8aa3b, v28
	v_rcp_f32_e32 v164, v139
	v_mul_f32_e32 v139, 0xbfb8aa3b, v33
	v_rcp_f32_e32 v0, v156
	v_rcp_f32_e32 v137, v157
	v_pk_mul_f32 v[156:157], v[156:157], v[158:159]
	v_exp_f32_e32 v158, v141
	v_mul_f32_e32 v141, 0xbfb8aa3b, v24
	v_exp_f32_e32 v139, v139
	v_pk_mul_f32 v[154:155], v[154:155], v[160:161]
	v_exp_f32_e32 v160, v141
	v_mul_f32_e32 v141, 0xbfb8aa3b, v20
	v_exp_f32_e32 v162, v141
	v_mul_f32_e32 v141, 0xbfb8aa3b, v29
	v_exp_f32_e32 v159, v141
	v_mul_f32_e32 v141, 0xbfb8aa3b, v25
	v_exp_f32_e32 v161, v141
	v_add_f32_e32 v139, 1.0, v139
	v_rcp_f32_e32 v165, v139
	v_mul_f32_e32 v141, 0xbfb8aa3b, v21
	v_exp_f32_e32 v163, v141
	v_pk_add_f32 v[158:159], v[158:159], 1.0 op_sel_hi:[1,0]
	v_pk_add_f32 v[160:161], v[160:161], 1.0 op_sel_hi:[1,0]
	v_rcp_f32_e32 v166, v158
	v_rcp_f32_e32 v167, v159
	v_pk_mul_f32 v[158:159], v[158:159], v[164:165]
	v_rcp_f32_e32 v164, v160
	v_rcp_f32_e32 v165, v161
	s_mov_b64 s[8:9], 0x140000
	v_pk_add_f32 v[162:163], v[162:163], 1.0 op_sel_hi:[1,0]
	v_cvt_pk_bf16_f32 v170, v146, v147
	v_cvt_pk_bf16_f32 v171, v158, v159
	v_lshl_add_u64 v[158:159], v[144:145], 0, s[8:9]
	s_mov_b32 s8, 0x141000
	v_rcp_f32_e32 v139, v162
	v_rcp_f32_e32 v141, v163
	v_pk_mul_f32 v[162:163], v[162:163], v[164:165]
	v_add_co_u32_e32 v164, vcc, s8, v144
	v_pk_mul_f32 v[160:161], v[160:161], v[166:167]
	s_nop 0
	v_addc_co_u32_e32 v165, vcc, 0, v145, vcc
	v_lshl_add_u64 v[180:181], v[164:165], 0, v[178:179]
	v_cvt_pk_bf16_f32 v174, v154, v155
	v_cvt_pk_bf16_f32 v175, v160, v161
	v_cvt_pk_bf16_f32 v172, v156, v157
	v_cvt_pk_bf16_f32 v173, v162, v163
	v_cvt_pk_bf16_f32 v176, v0, v137
	v_mul_f32_e32 v0, 0xbfb8aa3b, v14
	v_exp_f32_e32 v0, v0
	v_cvt_pk_bf16_f32 v177, v139, v141
	v_mul_f32_e32 v137, 0xbfb8aa3b, v10
	s_nop 1
	v_permlane16_swap_b32_e32 v170, v172
	v_permlane16_swap_b32_e32 v171, v173
	v_permlane16_swap_b32_e32 v174, v176
	v_permlane16_swap_b32_e32 v175, v177
	global_store_dwordx4 v[180:181], v[170:173], off offset:-4096
	global_store_dwordx4 v[180:181], v[174:177], off offset:-2048
	v_add_f32_e32 v0, 1.0, v0
	v_rcp_f32_e32 v158, v0
	v_mul_f32_e32 v0, 0xbfb8aa3b, v15
	v_exp_f32_e32 v146, v137
	v_mul_f32_e32 v137, 0xbfb8aa3b, v6
	v_exp_f32_e32 v0, v0
	v_exp_f32_e32 v154, v137
	v_mul_f32_e32 v137, 0xbfb8aa3b, v2
	v_exp_f32_e32 v156, v137
	v_mul_f32_e32 v137, 0xbfb8aa3b, v11
	v_exp_f32_e32 v147, v137
	v_mul_f32_e32 v137, 0xbfb8aa3b, v7
	v_exp_f32_e32 v155, v137
	v_add_f32_e32 v0, 1.0, v0
	v_rcp_f32_e32 v159, v0
	v_mul_f32_e32 v139, 0xbfb8aa3b, v16
	v_mul_f32_e32 v137, 0xbfb8aa3b, v3
	v_exp_f32_e32 v139, v139
	v_exp_f32_e32 v157, v137
	v_pk_add_f32 v[146:147], v[146:147], 1.0 op_sel_hi:[1,0]
	v_pk_add_f32 v[154:155], v[154:155], 1.0 op_sel_hi:[1,0]
	v_rcp_f32_e32 v160, v146
	v_rcp_f32_e32 v161, v147
	v_pk_mul_f32 v[146:147], v[146:147], v[158:159]
	v_rcp_f32_e32 v158, v154
	v_rcp_f32_e32 v159, v155
	v_add_f32_e32 v139, 1.0, v139
	v_pk_add_f32 v[156:157], v[156:157], 1.0 op_sel_hi:[1,0]
	v_mul_f32_e32 v141, 0xbfb8aa3b, v12
	v_rcp_f32_e32 v164, v139
	v_mul_f32_e32 v139, 0xbfb8aa3b, v17
	v_rcp_f32_e32 v0, v156
	v_rcp_f32_e32 v137, v157
	v_pk_mul_f32 v[156:157], v[156:157], v[158:159]
	v_exp_f32_e32 v158, v141
	v_mul_f32_e32 v141, 0xbfb8aa3b, v8
	v_exp_f32_e32 v139, v139
	v_pk_mul_f32 v[154:155], v[154:155], v[160:161]
	v_exp_f32_e32 v160, v141
	v_mul_f32_e32 v141, 0xbfb8aa3b, v4
	v_exp_f32_e32 v162, v141
	v_mul_f32_e32 v141, 0xbfb8aa3b, v13
	v_exp_f32_e32 v159, v141
	v_mul_f32_e32 v141, 0xbfb8aa3b, v9
	v_exp_f32_e32 v161, v141
	v_add_f32_e32 v139, 1.0, v139
	v_rcp_f32_e32 v165, v139
	v_mul_f32_e32 v141, 0xbfb8aa3b, v5
	v_exp_f32_e32 v163, v141
	v_pk_add_f32 v[158:159], v[158:159], 1.0 op_sel_hi:[1,0]
	v_pk_add_f32 v[160:161], v[160:161], 1.0 op_sel_hi:[1,0]
	v_rcp_f32_e32 v166, v158
	v_rcp_f32_e32 v167, v159
	v_pk_mul_f32 v[158:159], v[158:159], v[164:165]
	v_rcp_f32_e32 v164, v160
	v_rcp_f32_e32 v165, v161
	s_mov_b64 s[8:9], 0x160000
	v_pk_add_f32 v[162:163], v[162:163], 1.0 op_sel_hi:[1,0]
	v_cvt_pk_bf16_f32 v170, v146, v147
	v_cvt_pk_bf16_f32 v171, v158, v159
	v_lshl_add_u64 v[158:159], v[144:145], 0, s[8:9]
	s_mov_b32 s8, 0x160000
	v_rcp_f32_e32 v139, v162
	v_rcp_f32_e32 v141, v163
	v_pk_mul_f32 v[162:163], v[162:163], v[164:165]
	v_add_co_u32_e32 v164, vcc, s8, v144
	v_pk_mul_f32 v[160:161], v[160:161], v[166:167]
	s_nop 0
	v_addc_co_u32_e32 v165, vcc, 0, v145, vcc
	v_lshl_add_u64 v[180:181], v[164:165], 0, v[178:179]
	v_cvt_pk_bf16_f32 v174, v154, v155
	v_cvt_pk_bf16_f32 v175, v160, v161
	v_add_co_u32_e32 v144, vcc, 0x161000, v144
	v_cvt_pk_bf16_f32 v172, v156, v157
	v_cvt_pk_bf16_f32 v173, v162, v163
	v_addc_co_u32_e32 v145, vcc, 0, v145, vcc
	v_cvt_pk_bf16_f32 v176, v0, v137
	v_cvt_pk_bf16_f32 v177, v139, v141
	s_nop 1
	v_permlane16_swap_b32_e32 v170, v172
	v_permlane16_swap_b32_e32 v171, v173
	v_permlane16_swap_b32_e32 v174, v176
	v_permlane16_swap_b32_e32 v175, v177
	global_store_dwordx4 v[180:181], v[170:173], off
	global_store_dwordx4 v[180:181], v[174:177], off offset:2048
	s_cbranch_execnz .LBB0_807
